# per-iteration scalar setup (slot selects, DMA base addresses, loop counters) hoisted before the barrier so the post-barrier path starts with the V fragment reads
# baseline (speedup 1.0000x reference)
; #define LAS __attribute__((address_space(3)))
; #define VLOAD(ks, DST) do { const LAS unsigned char* vp_ = Vb + (ks) * 32; \
;         _Pragma("unroll") for (int nb = 0; nb < NB; ++nb) DST[nb] = *(const LAS bf16x8*)(vp_ + nb * 32 * VTP); } while (0)
; #define PVMMA(SRC, PF) do { _Pragma("unroll") for (int nb = 0; nb < NB; ++nb) o[nb] = __builtin_amdgcn_mfma_f32_32x32x16_bf16(SRC[nb], PF, o[nb], 0, 0, 0); } while (0)
; #define SBAR_() __builtin_amdgcn_sched_barrier(0)
; template <int MODE, bool FROZEN = false>
; __device__ __forceinline__ bool attn_unit(LAS unsigned char* lds, const Params& p, int l, int ua, int ub) {
;     ...
;     for (int t = 0; t < NT; ++t) {
;         if (t + 2 < NT) {
; #pragma unroll
;             for (int i = 0; i < NKC; ++i) *(LAS u32x4*)(lds + kdst[i] + (t & 1) * KBUF) = kr[i];
;         }
;         if (t + 1 < NT) {
; #pragma unroll
;             for (int i = 0; i < NVC; ++i) { *(LAS u32x2*)(lds + vdst[i] + ((t + 1) & 1) * VBUF) = (u32x2){vr[i].x, vr[i].y}; *(LAS u32x2*)(lds + vdst[i] + ((t + 1) & 1) * VBUF + 16) = (u32x2){vr[i].z, vr[i].w}; }
;         }
;         {
;             const size_t advk = (size_t)min(t + 3, NT - 1) * 64 * NPROJ, advv = (size_t)min(t + 2, NT - 1) * 64;
; #pragma unroll
;             for (int i = 0; i < NKC; ++i) kr[i] = *(const u32x4*)(kvbase + advk + ksrc[i]);
; #pragma unroll
;             for (int i = 0; i < NVC; ++i) vr[i] = *(const u32x4*)(vtbase + advv + vsrc[i]);
;         }
;         f32x16 sA0 = sB0, sA1 = sB1;
;         const float c2 = cbB - m_run;
;         const LAS unsigned char* Vb = lds + OFF_V + (t & 1) * VBUF + vlane_off;
;         const LAS unsigned char* Kb = lds + OFF_K + ((t + 1) & 1) * KBUF + klane_off;
;     ...
;         bf16x8 kf0[4], kf1[4], va[NB], vb[NB], pf0, pf1; float ps0, ps1, ps2, ps3;
;         VLOAD(0, va);
;         EXPCVT(0, pf0, ps0);
;         SBAR_();
;         VLOAD(1, vb); PVMMA(va, pf0); EXPCVT(1, pf1, ps1); _Pragma("unroll") for (int g_ = 0; g_ < NB; ++g_) { __builtin_amdgcn_sched_group_barrier(0x008, 1, 0); __builtin_amdgcn_sched_group_barrier(0x100, 1, 0); __builtin_amdgcn_sched_group_barrier(0x400, 8 / NB, 0); __builtin_amdgcn_sched_group_barrier(0x002, 12 / NB, 0); } SBAR_();
.LBB0_117:
	s_add_i32 s14, s4, 1
	s_bitcmp1_b32 s14, 0
	s_cselect_b32 s15, 0x4400, 0
	s_cselect_b32 s100, 0, 0x4800
	s_sub_i32 s5, 0x4400, s15
	s_min_i32 s10, s4, 0xfd
	s_mul_i32 s10, s10, 0x78000
	s_add_u32 s10, s34, s10
	s_addc_u32 s11, s35, 0
	s_add_u32 s10, s10, s99
	s_addc_u32 s11, s11, 0
	s_lshl_b32 s0, s14, 7
	s_add_u32 s0, s6, s0
	s_addc_u32 s1, s7, 0
	s_add_u32 s0, s0, s101
	s_addc_u32 s1, s1, 0
.LBB0_118:
	v_add_u32_e32 v194, s100, v101
	ds_read_b128 v[112:115], v194 offset:34816
	ds_read_b128 v[170:173], v194 offset:39424
	ds_read_b128 v[174:177], v194 offset:44032
	ds_read_b128 v[178:181], v194 offset:48640
	v_exp_f32_e32 v103, v16
	v_exp_f32_e32 v104, v17
	v_mfma_f32_32x32x16_bf16 v[52:67], v[236:239], v[244:247], v[52:67]
	v_exp_f32_e32 v105, v18
	v_exp_f32_e32 v106, v19
	v_cvt_pk_bf16_f32 v16, v103, v104
	v_mfma_f32_32x32x16_bf16 v[36:51], v[218:221], v[244:247], v[36:51]
	s_add_i32 m0, s5, s98
	s_nop 0
	global_load_lds_dwordx4 v132, s[10:11]
	v_exp_f32_e32 v107, v20
	v_exp_f32_e32 v108, v21
	v_cvt_pk_bf16_f32 v17, v105, v106
	v_mfma_f32_32x32x16_bf16 v[84:99], v[222:225], v[244:247], v[84:99]
	s_add_i32 m0, m0, 0x400
	s_nop 0
	global_load_lds_dwordx4 v133, s[10:11]
	v_exp_f32_e32 v109, v22
	v_exp_f32_e32 v110, v23
	v_cvt_pk_bf16_f32 v18, v107, v108
	v_mfma_f32_32x32x16_bf16 v[68:83], v[248:251], v[244:247], v[68:83]
	s_cmp_lg_u32 s98, 0x1000
	s_cbranch_scc1 .Lkdma_skip
	s_add_i32 m0, s5, 0x4000
	s_nop 0
	global_load_lds_dwordx4 v134, s[10:11]

; #define LAS __attribute__((address_space(3)))
; template <int MODE, bool FROZEN = false>
; __device__ __forceinline__ bool attn_unit(LAS unsigned char* lds, const Params& p, int l, int ua, int ub) {
;     ...
;     for (int t = 0; t < NT; ++t) {
;         if (t + 2 < NT) {
; #pragma unroll
;             for (int i = 0; i < NKC; ++i) *(LAS u32x4*)(lds + kdst[i] + (t & 1) * KBUF) = kr[i];
;         }
;         if (t + 1 < NT) {
; #pragma unroll
;             for (int i = 0; i < NVC; ++i) { *(LAS u32x2*)(lds + vdst[i] + ((t + 1) & 1) * VBUF) = (u32x2){vr[i].x, vr[i].y}; *(LAS u32x2*)(lds + vdst[i] + ((t + 1) & 1) * VBUF + 16) = (u32x2){vr[i].z, vr[i].w}; }
;         }
;         {
;             const size_t advk = (size_t)min(t + 3, NT - 1) * 64 * NPROJ, advv = (size_t)min(t + 2, NT - 1) * 64;
; #pragma unroll
;             for (int i = 0; i < NKC; ++i) kr[i] = *(const u32x4*)(kvbase + advk + ksrc[i]);
; #pragma unroll
;             for (int i = 0; i < NVC; ++i) vr[i] = *(const u32x4*)(vtbase + advv + vsrc[i]);
;         }
;         f32x16 sA0 = sB0, sA1 = sB1;
;         const float c2 = cbB - m_run;
;         const LAS unsigned char* Vb = lds + OFF_V + (t & 1) * VBUF + vlane_off;
;         const LAS unsigned char* Kb = lds + OFF_K + ((t + 1) & 1) * KBUF + klane_off;
;     ...
;         l_run += ps;
;         if (t + 1 < NT) { ATT_BIAS(t + 1, tmr); ATT_UPD(tmr); }
;         asm volatile("s_waitcnt lgkmcnt(0)" ::: "memory"); __builtin_amdgcn_s_barrier(); asm volatile("" ::: "memory");
;     }
.LBB0_123:
	s_addk_i32 s13, 0x100
	s_sub_i32 s8, s8, 64
	s_add_i32 s12, s12, 64
	s_mov_b32 s4, s14
	s_add_i32 s14, s4, 1
	s_bitcmp1_b32 s14, 0
	s_cselect_b32 s15, 0x4400, 0
	s_cselect_b32 s100, 0, 0x4800
	s_sub_i32 s5, 0x4400, s15
	s_min_i32 s10, s4, 0xfd
	s_mul_i32 s10, s10, 0x78000
	s_add_u32 s10, s34, s10
	s_addc_u32 s11, s35, 0
	s_add_u32 s10, s10, s99
	s_addc_u32 s11, s11, 0
	s_lshl_b32 s0, s14, 7
	s_add_u32 s0, s6, s0
	s_addc_u32 s1, s7, 0
	s_add_u32 s0, s0, s101
	s_addc_u32 s1, s1, 0
	s_cmpk_eq_u32 s13, 0xff00
	s_waitcnt vmcnt(0) lgkmcnt(0)
	s_barrier
	s_cbranch_scc1 .LBB0_125
	s_branch .LBB0_118
